# retention: the wave half with more live key blocks (causal mask) runs at raised static priority for the item; on top of v17
# baseline (speedup 1.0000x reference)
; #define LAS __attribute__((address_space(3)))
; __device__ __forceinline__ void retention_item(LAS unsigned char* lds, const Params& p, int item) {
;     int tid_ = threadIdx.x; asm volatile("" : "+v"(tid_));
;     const int tid = tid_, wid = __builtin_amdgcn_readfirstlane(tid >> 6), lane = tid & 63, fr = lane & 15, fq = lane >> 4;
;     const int b = item >> 3, h = (item >> 1) & 3, dir = item & 1;
;     const float l2g = p.ret_log_decay[dir * 4 + h] * 1.4426950408889634f;
;     const float decayC = exp2f(128.0f * l2g);
;     LAS bf16_t* Ks = (LAS bf16_t*)lds;
;     LAS bf16_t* Vts = Ks + 128 * 72;
;     LAS bf16_t* Kzs = Vts + 128 * 136;
;     LAS bf16_t* Sts = Kzs + 64 * 136;
;     const bf16_t* P = (const bf16_t*)(p.ws + OFF_P);
;     bf16_t* CAT = (bf16_t*)(p.ws + OFF_A);
;     const int c = 16 * wid + fr;
;     const float xi = exp2f((float)(dir ? (128 - c) : (c + 1)) * l2g);
;     f32x4 accSt[4];
; #pragma unroll
;     for (int db = 0; db < 4; ++db) accSt[db] = (f32x4){0.f, 0.f, 0.f, 0.f};
;     u32x4 pk[2], pv[4], pz[2]; bf16x8 pq[2]; u32x2 pg[8];
; #pragma unroll
;     for (int q = 0; q < 2; ++q) { pk[q] = (u32x4){0u, 0u, 0u, 0u}; pq[q] = __builtin_bit_cast(bf16x8, pk[q]); }
; #pragma unroll
;     for (int q = 0; q < 8; ++q) pg[q] = (u32x2){0u, 0u};
;     {   const RetStep r = ret_step(p, 0, b, dir);
; #pragma unroll
;         for (int q = 0; q < 4; ++q) { const int pc = tid + q * 512, row = pc >> 4, seg = pc & 15; pv[q] = *(const u32x4*)(r.vt + (size_t)(128 * h + row) * r.NT + r.tok0 + seg * 8); }
; #pragma unroll
;         for (int q = 0; q < 2; ++q) { const int pc = tid + q * 512, row = pc >> 4, seg = pc & 15; pz[q] = *(const u32x4*)(r.kz + (size_t)(dir * 256 + 64 * h + row) * r.NT + r.tok0 + seg * 8); }
;     }
.LBB0_773:
	v_mov_b32_e32 v31, v200
	s_and_b32 s10, s50, 1
	v_readfirstlane_b32 s0, v31
	s_ashr_i32 s6, s0, 6
	s_lshr_b32 s0, s6, 2
	s_xor_b32 s0, s0, s10
	s_cmp_eq_u32 s0, 1
	s_cbranch_scc0 .Lret_prio_lo
	s_setprio 1
	s_branch .Lret_prio_done
.Lret_prio_lo:
	s_setprio 0
.Lret_prio_done:
	s_cmp_lt_i32 s6, 6
	s_cselect_b64 s[0:1], -1, 0
	s_cmp_lt_i32 s6, 8
	s_cselect_b64 s[2:3], -1, 0
	s_cmp_gt_i32 s6, 5
	s_cselect_b64 s[4:5], -1, 0
	s_cmp_eq_u32 s10, 0
	s_cselect_b64 vcc, -1, 0
	s_cmp_gt_i32 s6, 3
	s_waitcnt vmcnt(5)
	v_cndmask_b32_e64 v0, 0, 1, s[2:3]
	v_cndmask_b32_e64 v1, 0, 1, s[4:5]
	s_cselect_b64 s[2:3], -1, 0
	s_cmp_eq_u32 s10, 0
	v_cndmask_b32_e32 v37, v0, v1, vcc
	s_cselect_b64 vcc, -1, 0
	s_cmp_lt_i32 s6, 4
	v_cndmask_b32_e64 v0, 0, 1, s[0:1]
	s_cselect_b64 s[0:1], -1, 0
	s_cmp_gt_i32 s6, 1
	v_cndmask_b32_e64 v1, 0, 1, s[2:3]
	s_cselect_b64 s[2:3], -1, 0
	s_cmp_eq_u32 s10, 0
	v_cndmask_b32_e32 v39, v0, v1, vcc
	s_cselect_b64 vcc, -1, 0
	s_cmp_lt_i32 s6, 2
	v_cndmask_b32_e64 v0, 0, 1, s[0:1]
	s_cselect_b64 s[0:1], -1, 0
	s_cmp_gt_i32 s6, -1
	s_cselect_b64 s[4:5], -1, 0
	s_cmp_eq_u32 s10, 0
	v_cndmask_b32_e64 v1, 0, 1, s[2:3]
	s_cselect_b64 s[2:3], -1, 0
	s_bfe_u32 s12, s50, 0x20001
	v_cndmask_b32_e32 v40, v0, v1, vcc
	v_cndmask_b32_e64 v0, 0, 1, s[0:1]
	s_lshl_b32 s0, s12, 2
	s_lshl_b32 s1, s10, 4
	v_cndmask_b32_e64 v1, 0, 1, s[4:5]
	s_or_b32 s0, s1, s0
	v_readlane_b32 s16, v254, 0
	v_cndmask_b32_e64 v41, v0, v1, s[2:3]
	v_mov_b32_e32 v0, s0
	v_readlane_b32 s22, v254, 6
	v_readlane_b32 s23, v254, 7
	s_mov_b32 s15, 0xc2fc0000
	s_lshl_b32 s11, s6, 4
	s_ashr_i32 s4, s50, 3
	v_and_b32_e32 v27, 15, v31
	v_or_b32_e32 v110, s11, v27
	global_load_dword v0, v0, s[22:23]
	v_sub_u32_e32 v1, 0x80, v110
	v_add_u32_e32 v2, 1, v110
	v_cndmask_b32_e64 v1, v1, v2, s[2:3]
	v_cvt_f32_i32_e32 v25, v1
	v_readlane_b32 s17, v254, 1
	v_readlane_b32 s18, v254, 2
	v_readlane_b32 s19, v254, 3
	v_readlane_b32 s20, v254, 4
	v_readlane_b32 s21, v254, 5
	v_readlane_b32 s24, v254, 8
	v_readlane_b32 s25, v254, 9
	v_readlane_b32 s26, v254, 10
	v_readlane_b32 s27, v254, 11
	v_readlane_b32 s28, v254, 12
	v_readlane_b32 s29, v254, 13
	v_readlane_b32 s30, v254, 14
	v_readlane_b32 s31, v254, 15
	v_writelane_b32 v254, s50, 22
	v_ashrrev_i32_e32 v34, 4, v31
	v_bfe_u32 v29, v31, 4, 2
	v_lshlrev_b32_e32 v32, 4, v29
	s_waitcnt vmcnt(4)
	v_add_u32_e32 v8, 0x400, v31
	v_add_u32_e32 v128, 0, v32
	s_movk_i32 s84, 0x110
	v_add_u32_e32 v35, 0x200, v31
	v_ashrrev_i32_e32 v44, 4, v8
	v_lshlrev_b32_e32 v42, 2, v29
	v_and_b32_e32 v41, 1, v41
	v_ashrrev_i32_e32 v36, 4, v35
	v_ashrrev_i32_e32 v140, 3, v35
	v_mul_lo_u32 v35, v44, s84
	s_waitcnt vmcnt(3)
	v_add_u32_e32 v14, 0x600, v31
	v_ashrrev_i32_e32 v45, 4, v14
	v_or_b32_e32 v43, s11, v42
	v_and_b32_e32 v40, 1, v40
	v_cmp_eq_u32_e64 s[22:23], 1, v40
	v_or_b32_e32 v40, 32, v42
	v_and_b32_e32 v39, 1, v39
	v_cmp_eq_u32_e64 s[42:43], 1, v39
	v_or_b32_e32 v39, 64, v42
	v_and_b32_e32 v37, 1, v37
	v_cmp_eq_u32_e64 s[60:61], 1, v37
	v_or_b32_e32 v37, 0x60, v42
	v_mul_u32_u24_e32 v193, 0x110, v27
	v_mov_b32_e32 v33, v109
	v_ashrrev_i32_e32 v138, 3, v31
	s_movk_i32 s85, 0x90
	v_mov_b32_e32 v56, v109
	v_mov_b32_e32 v57, v109
	v_mov_b32_e32 v58, v109
	v_mov_b32_e32 v59, v109
	v_ashrrev_i32_e32 v111, 31, v110
	s_waitcnt vmcnt(1)
	v_mov_b32_e32 v146, v109
	v_mov_b32_e32 v147, v109
	v_mov_b64_e32 v[62:63], v[58:59]
	v_ashrrev_i32_e32 v139, 31, v138
	v_ashrrev_i32_e32 v141, 31, v140
	s_mov_b32 s94, s91
	v_mov_b64_e32 v[60:61], v[56:57]
	v_mov_b64_e32 v[160:161], v[146:147]
	v_mov_b64_e32 v[158:159], v[146:147]
	v_mov_b64_e32 v[156:157], v[146:147]
	v_mov_b64_e32 v[154:155], v[146:147]
	v_mov_b64_e32 v[152:153], v[146:147]
	v_mov_b64_e32 v[150:151], v[146:147]
	v_mov_b64_e32 v[148:149], v[146:147]
	s_mov_b32 s95, s91
	v_mov_b32_e32 v46, v109
	v_mov_b32_e32 v47, v109
	s_waitcnt vmcnt(0)
	v_mul_f32_e32 v38, 0x3fb8aa3b, v0
	v_mul_f32_e32 v0, 0x43000000, v38
	v_cmp_gt_f32_e32 vcc, s15, v0
	s_and_b64 s[0:1], vcc, exec
	s_cselect_b32 s0, 0xffffffc0, 0
	v_cndmask_b32_e32 v0, 0, v129, vcc
	v_fmac_f32_e32 v0, 0x43000000, v38
	v_exp_f32_e32 v0, v0
	s_ashr_i32 s5, s4, 31
	s_lshl_b32 s14, s10, 7
	s_lshl_b32 s13, s12, 7
	v_ldexp_f32 v112, v0, s0
	s_lshl_b64 s[0:1], s[4:5], 8
	s_or_b32 s6, s0, s14
	s_mov_b32 s7, s1
	s_lshl_b64 s[6:7], s[6:7], 1
	v_lshlrev_b32_e32 v0, 3, v31
	s_add_u32 s8, s62, s6
	v_and_b32_e32 v24, 0x78, v0
	s_addc_u32 s9, s63, s7
	v_lshlrev_b32_e32 v108, 1, v24
	v_lshl_add_u64 v[12:13], s[8:9], 0, v[108:109]
	s_lshl_b32 s8, s10, 8
	s_lshl_b32 s9, s12, 6
	s_or_b32 s8, s9, s8
	v_mul_f32_e32 v26, v38, v25
	s_add_u32 s6, s70, s6
	s_addc_u32 s7, s71, s7
	v_cmp_gt_f32_e32 vcc, s15, v26
	s_lshl_b64 s[88:89], s[4:5], 11
	s_xor_b32 s4, s14, 0x80
	v_cndmask_b32_e32 v26, 0, v129, vcc
	s_or_b32 s4, s0, s4
	v_fmac_f32_e32 v26, v38, v25
	s_mov_b32 s5, s1
	s_add_u32 s78, s82, s13
	v_exp_f32_e32 v25, v26
	v_writelane_b32 v254, s4, 23
	s_addc_u32 s79, s83, 0
	s_lshl_b32 s80, s10, 10
	v_writelane_b32 v254, s5, 24
	s_add_u32 s4, s96, s80
	v_add_u32_e32 v114, s13, v34
	s_addc_u32 s5, s97, 0
	s_lshl_b32 s81, s12, 8
	v_ashrrev_i32_e32 v115, 31, v114
	v_cndmask_b32_e32 v26, 0, v162, vcc
	s_add_u32 s4, s4, s81
	v_lshlrev_b64 v[0:1], 14, v[114:115]
	v_lshl_add_u64 v[20:21], s[6:7], 0, v[108:109]
	v_ldexp_f32 v115, v25, v26
	v_add_u32_e32 v25, 0, v108
	v_lshlrev_b32_e32 v108, 3, v29
	s_addc_u32 s5, s5, 0
	v_lshl_add_u64 v[130:131], s[4:5], 0, v[108:109]
	v_mad_u64_u32 v[136:137], s[4:5], v110, s84, v[128:129]
	v_add_u32_e32 v118, s13, v44
	v_cmp_eq_u32_e64 s[4:5], 1, v41
	v_sub_u32_e32 v41, v42, v110
	v_sub_u32_e32 v44, v110, v42
	v_readlane_b32 s6, v254, 45
; __device__ __forceinline__ void retention_item(LAS unsigned char* lds, const Params& p, int item) {
;     ...
;         for (int q = 0; q < 4; ++q) { const int pc = tid + q * 512, row = pc >> 4, seg = pc & 15; pv[q] = *(const u32x4*)(r.vt + (size_t)(128 * h + row) * r.NT + r.tok0 + seg * 8); }
; #pragma unroll
;         for (int q = 0; q < 2; ++q) { const int pc = tid + q * 512, row = pc >> 4, seg = pc & 15; pz[q] = *(const u32x4*)(r.kz + (size_t)(dir * 256 + 64 * h + row) * r.NT + r.tok0 + seg * 8); }
;     ...
;                     for (int q = 0; q < 2; ++q) { const int mb = 2 * ks + q;
; #pragma unroll
;                         for (int r = 0; r < 4; ++r) { const int m = 16 * mb + 4 * fq + r; const int diff = dir ? (m - c) : (c - m); sc[q][r] = diff >= 0 ? sc[q][r] * __builtin_amdgcn_exp2f((float)diff * l2g) : 0.f; }
;                     }
	v_cndmask_b32_e64 v41, v41, v44, s[2:3]
	v_ashrrev_i32_e32 v119, 31, v118
	v_add_u32_e32 v29, s6, v32
	v_lshl_add_u32 v30, v27, 1, s6
	v_cmp_lt_i32_e64 s[6:7], -1, v41
	v_cvt_f32_u32_e32 v41, v41
	v_lshlrev_b64 v[8:9], 14, v[118:119]
	v_add_u32_e32 v122, s8, v34
	v_add_u32_e32 v124, s8, v36
	v_mul_f32_e32 v41, v38, v41
	v_exp_f32_e32 v119, v41
	v_or_b32_e32 v41, 1, v42
	v_sub_u32_e32 v44, v41, v110
	v_sub_u32_e32 v41, v110, v41
	v_cndmask_b32_e64 v41, v44, v41, s[2:3]
	v_cmp_lt_i32_e64 s[8:9], -1, v41
	v_cvt_f32_u32_e32 v41, v41
	v_add_u32_e32 v120, s13, v45
	v_ashrrev_i32_e32 v121, 31, v120
	v_lshlrev_b64 v[14:15], 14, v[120:121]
	v_mul_f32_e32 v41, v38, v41
	v_exp_f32_e32 v121, v41
	v_or_b32_e32 v41, 2, v42
	v_sub_u32_e32 v44, v41, v110
	v_sub_u32_e32 v41, v110, v41
	v_cndmask_b32_e64 v41, v44, v41, s[2:3]
	v_cmp_lt_i32_e64 s[10:11], -1, v41
	v_cvt_f32_u32_e32 v41, v41
	v_ashrrev_i32_e32 v123, 31, v122
	v_lshlrev_b64 v[16:17], 14, v[122:123]
	v_add_u32_e32 v116, s13, v36
	v_mul_f32_e32 v41, v38, v41
	v_exp_f32_e32 v123, v41
	v_or_b32_e32 v41, 3, v42
	v_sub_u32_e32 v44, v41, v110
	v_sub_u32_e32 v41, v110, v41
	v_cndmask_b32_e64 v41, v44, v41, s[2:3]
	v_cmp_lt_i32_e64 s[12:13], -1, v41
	v_cvt_f32_u32_e32 v41, v41
	v_ashrrev_i32_e32 v125, 31, v124
	v_lshlrev_b64 v[22:23], 14, v[124:125]
	v_ashrrev_i32_e32 v117, 31, v116
	v_mul_f32_e32 v41, v38, v41
	v_exp_f32_e32 v125, v41
	v_or_b32_e32 v41, 16, v42
	v_sub_u32_e32 v44, v41, v110
	v_sub_u32_e32 v41, v110, v41
	v_cndmask_b32_e64 v41, v44, v41, s[2:3]
	v_cmp_lt_i32_e64 s[14:15], -1, v41
	v_cvt_f32_u32_e32 v41, v41
	v_lshlrev_b64 v[4:5], 14, v[116:117]
	v_lshl_add_u64 v[0:1], v[12:13], 0, v[0:1]
	v_lshl_add_u64 v[4:5], v[12:13], 0, v[4:5]
	v_mul_f32_e32 v41, v38, v41
	v_exp_f32_e32 v137, v41
	v_or_b32_e32 v41, 17, v42
	v_sub_u32_e32 v44, v41, v110
	v_sub_u32_e32 v41, v110, v41
	v_cndmask_b32_e64 v41, v44, v41, s[2:3]
	v_cmp_lt_i32_e64 s[16:17], -1, v41
	v_cvt_f32_u32_e32 v41, v41
	v_lshl_add_u64 v[8:9], v[12:13], 0, v[8:9]
	v_lshl_add_u64 v[12:13], v[12:13], 0, v[14:15]
	v_lshl_add_u64 v[16:17], v[20:21], 0, v[16:17]
	v_mul_f32_e32 v41, v38, v41
	v_exp_f32_e32 v166, v41
	v_or_b32_e32 v41, 18, v42
	v_sub_u32_e32 v44, v41, v110
	v_sub_u32_e32 v41, v110, v41
	v_cndmask_b32_e64 v41, v44, v41, s[2:3]
	v_cmp_lt_i32_e64 s[18:19], -1, v41
	v_cvt_f32_u32_e32 v41, v41
	v_lshl_add_u64 v[20:21], v[20:21], 0, v[22:23]
	global_load_dwordx4 v[0:3], v[0:1], off
	v_lshlrev_b32_e32 v26, 4, v31
	v_mul_f32_e32 v41, v38, v41
	v_exp_f32_e32 v167, v41
	v_or_b32_e32 v41, 19, v42
	v_sub_u32_e32 v44, v41, v110
	v_sub_u32_e32 v41, v110, v41
	v_cndmask_b32_e64 v41, v44, v41, s[2:3]
	v_cmp_lt_i32_e64 s[20:21], -1, v41
	v_cvt_f32_u32_e32 v41, v41
	global_load_dwordx4 v[4:7], v[4:5], off
	v_mul_u32_u24_e32 v117, 0x90, v27
	global_load_dwordx4 v[8:11], v[8:9], off
	v_mul_f32_e32 v41, v38, v41
	v_exp_f32_e32 v168, v41
	v_sub_u32_e32 v41, v40, v110
	v_sub_u32_e32 v40, v110, v40
	v_cndmask_b32_e64 v40, v41, v40, s[2:3]
	v_cmp_lt_i32_e64 s[24:25], -1, v40
	v_cvt_f32_u32_e32 v40, v40
	global_load_dwordx4 v[12:15], v[12:13], off
	v_and_b32_e32 v26, 0x70, v26
	global_load_dwordx4 v[16:19], v[16:17], off
	v_mul_f32_e32 v40, v38, v40
	v_exp_f32_e32 v169, v40
	v_or_b32_e32 v40, 33, v42
	v_sub_u32_e32 v41, v40, v110
	v_sub_u32_e32 v40, v110, v40
	v_cndmask_b32_e64 v40, v41, v40, s[2:3]
	v_cmp_lt_i32_e64 s[26:27], -1, v40
	v_cvt_f32_u32_e32 v40, v40
	global_load_dwordx4 v[20:23], v[20:21], off
	v_lshl_add_u64 v[126:127], s[78:79], 0, v[32:33]
	v_add_u32_e32 v28, 0, v26
	v_mul_f32_e32 v40, v38, v40
	v_exp_f32_e32 v170, v40
	v_or_b32_e32 v40, 34, v42
	v_sub_u32_e32 v41, v40, v110
	v_sub_u32_e32 v40, v110, v40
	v_cndmask_b32_e64 v40, v41, v40, s[2:3]
	v_cmp_lt_i32_e64 s[28:29], -1, v40
	v_cvt_f32_u32_e32 v40, v40
	v_mul_lo_u32 v31, v138, s85
	v_mul_lo_u32 v32, v140, s85
	v_mul_lo_u32 v33, v34, s84
	v_mul_f32_e32 v40, v38, v40
	v_exp_f32_e32 v171, v40
	v_or_b32_e32 v40, 35, v42
	v_sub_u32_e32 v41, v40, v110
	v_sub_u32_e32 v40, v110, v40
	v_cndmask_b32_e64 v40, v41, v40, s[2:3]
	v_cmp_lt_i32_e64 s[30:31], -1, v40
	v_cvt_f32_u32_e32 v40, v40
	v_mul_lo_u32 v34, v36, s84
	v_mul_lo_u32 v36, v45, s84
	v_add3_u32 v194, 0, v193, v108
	v_mul_f32_e32 v40, v38, v40
	v_exp_f32_e32 v172, v40
	v_or_b32_e32 v40, 48, v42
	v_sub_u32_e32 v41, v40, v110
	v_sub_u32_e32 v40, v110, v40
	v_cndmask_b32_e64 v40, v41, v40, s[2:3]
	v_cmp_lt_i32_e64 s[34:35], -1, v40
	v_cvt_f32_u32_e32 v40, v40
	v_add_u32_e32 v204, v28, v31
	v_add_u32_e32 v205, v28, v32
	v_add_u32_e32 v206, v25, v33
	v_mul_f32_e32 v40, v38, v40
	v_exp_f32_e32 v173, v40
	v_or_b32_e32 v40, 49, v42
	v_sub_u32_e32 v41, v40, v110
	v_sub_u32_e32 v40, v110, v40
	v_cndmask_b32_e64 v40, v41, v40, s[2:3]
	v_cmp_lt_i32_e64 s[36:37], -1, v40
	v_cvt_f32_u32_e32 v40, v40
	v_add_u32_e32 v207, v25, v34
	v_add_u32_e32 v208, v25, v35
	v_add_u32_e32 v209, v25, v36
	v_mul_f32_e32 v40, v38, v40
	v_exp_f32_e32 v174, v40
	v_or_b32_e32 v40, 50, v42
	v_sub_u32_e32 v41, v40, v110
	v_sub_u32_e32 v40, v110, v40
	v_cndmask_b32_e64 v40, v41, v40, s[2:3]
	v_cmp_lt_i32_e64 s[38:39], -1, v40
	v_cvt_f32_u32_e32 v40, v40
	v_add_u32_e32 v210, v29, v117
	v_lshl_add_u64 v[132:133], s[88:89], 0, v[110:111]
	v_mov_b32_e32 v134, v112
	v_mul_f32_e32 v40, v38, v40
	v_exp_f32_e32 v175, v40
	v_or_b32_e32 v40, 51, v42
; __device__ __forceinline__ void retention_item(LAS unsigned char* lds, const Params& p, int item) {
;     ...
;     const int c = 16 * wid + fr;
;     const float xi = exp2f((float)(dir ? (128 - c) : (c + 1)) * l2g);
;     f32x4 accSt[4];
; #pragma unroll
;     for (int db = 0; db < 4; ++db) accSt[db] = (f32x4){0.f, 0.f, 0.f, 0.f};
;     ...
;                     for (int q = 0; q < 2; ++q) { const int mb = 2 * ks + q;
; #pragma unroll
;                         for (int r = 0; r < 4; ++r) { const int m = 16 * mb + 4 * fq + r; const int diff = dir ? (m - c) : (c - m); sc[q][r] = diff >= 0 ? sc[q][r] * __builtin_amdgcn_exp2f((float)diff * l2g) : 0.f; }
;                     }
	v_sub_u32_e32 v41, v40, v110
	v_sub_u32_e32 v40, v110, v40
	v_cndmask_b32_e64 v40, v41, v40, s[2:3]
	v_cmp_lt_i32_e64 s[40:41], -1, v40
	v_cvt_f32_u32_e32 v40, v40
	v_mov_b32_e32 v135, v112
	v_add_u32_e32 v195, 0x1100, v194
	v_add_u32_e32 v196, 0x2200, v194
	v_mul_f32_e32 v40, v38, v40
	v_exp_f32_e32 v176, v40
	v_sub_u32_e32 v40, v39, v110
	v_sub_u32_e32 v39, v110, v39
	v_cndmask_b32_e64 v39, v40, v39, s[2:3]
	v_cmp_lt_i32_e64 s[44:45], -1, v39
	v_cvt_f32_u32_e32 v39, v39
	v_add_u32_e32 v197, 0x3300, v194
	v_add_u32_e32 v198, 0x4400, v194
	v_add_u32_e32 v199, 0x5500, v194
	v_mul_f32_e32 v39, v38, v39
	v_exp_f32_e32 v177, v39
	v_or_b32_e32 v39, 0x41, v42
	v_sub_u32_e32 v40, v39, v110
	v_sub_u32_e32 v39, v110, v39
	v_cndmask_b32_e64 v39, v40, v39, s[2:3]
	v_cmp_lt_i32_e64 s[46:47], -1, v39
	v_cvt_f32_u32_e32 v39, v39
	v_add_u32_e32 v202, 0x7700, v194
	v_mov_b32_e32 v41, v109
	v_mov_b32_e32 v32, v109
	v_mul_f32_e32 v39, v38, v39
	v_exp_f32_e32 v178, v39
	v_or_b32_e32 v39, 0x42, v42
	v_sub_u32_e32 v40, v39, v110
	v_sub_u32_e32 v39, v110, v39
	v_cndmask_b32_e64 v39, v40, v39, s[2:3]
	v_cmp_lt_i32_e64 s[48:49], -1, v39
	v_cvt_f32_u32_e32 v39, v39
	v_mov_b32_e32 v33, v109
	v_mov_b32_e32 v34, v109
	v_mov_b32_e32 v35, v109
	v_mul_f32_e32 v39, v38, v39
	v_exp_f32_e32 v179, v39
	v_or_b32_e32 v39, 0x43, v42
	v_sub_u32_e32 v40, v39, v110
	v_sub_u32_e32 v39, v110, v39
	v_cndmask_b32_e64 v39, v40, v39, s[2:3]
	v_cmp_lt_i32_e64 s[50:51], -1, v39
	v_cvt_f32_u32_e32 v39, v39
	v_mov_b32_e32 v36, v109
	v_mov_b32_e32 v44, v109
	v_mov_b32_e32 v45, v109
	v_mul_f32_e32 v39, v38, v39
	v_exp_f32_e32 v180, v39
	v_or_b32_e32 v39, 0x50, v42
	v_sub_u32_e32 v40, v39, v110
	v_sub_u32_e32 v39, v110, v39
	v_cndmask_b32_e64 v39, v40, v39, s[2:3]
	v_cmp_lt_i32_e64 s[52:53], -1, v39
	v_cvt_f32_u32_e32 v39, v39
	v_mul_f32_e32 v39, v38, v39
	v_exp_f32_e32 v181, v39
	v_or_b32_e32 v39, 0x51, v42
	v_sub_u32_e32 v40, v39, v110
	v_sub_u32_e32 v39, v110, v39
	v_cndmask_b32_e64 v39, v40, v39, s[2:3]
	v_cmp_lt_i32_e64 s[54:55], -1, v39
	v_cvt_f32_u32_e32 v39, v39
	v_mul_f32_e32 v39, v38, v39
	v_exp_f32_e32 v182, v39
	v_or_b32_e32 v39, 0x52, v42
	v_sub_u32_e32 v40, v39, v110
	v_sub_u32_e32 v39, v110, v39
	v_cndmask_b32_e64 v39, v40, v39, s[2:3]
	v_cmp_lt_i32_e64 s[56:57], -1, v39
	v_cvt_f32_u32_e32 v39, v39
	v_mul_f32_e32 v39, v38, v39
	v_exp_f32_e32 v183, v39
	v_or_b32_e32 v39, 0x53, v42
	v_sub_u32_e32 v40, v39, v110
	v_sub_u32_e32 v39, v110, v39
	v_cndmask_b32_e64 v39, v40, v39, s[2:3]
	v_sub_u32_e32 v40, v37, v110
	v_sub_u32_e32 v37, v110, v37
	v_cndmask_b32_e64 v37, v40, v37, s[2:3]
	v_cmp_lt_i32_e64 s[62:63], -1, v37
	v_cvt_f32_u32_e32 v37, v37
	v_cmp_lt_i32_e64 s[58:59], -1, v39
	v_cvt_f32_u32_e32 v39, v39
	v_mul_f32_e32 v37, v38, v37
	v_exp_f32_e32 v185, v37
	v_or_b32_e32 v37, 0x61, v42
	v_sub_u32_e32 v40, v37, v110
	v_sub_u32_e32 v37, v110, v37
	v_cndmask_b32_e64 v37, v40, v37, s[2:3]
	v_cmp_lt_i32_e64 s[64:65], -1, v37
	v_cvt_f32_u32_e32 v37, v37
	v_mul_f32_e32 v39, v38, v39
	v_exp_f32_e32 v184, v39
	v_or_b32_e32 v39, 0x60, v27
	v_mul_f32_e32 v37, v38, v37
	v_exp_f32_e32 v186, v37
	v_or_b32_e32 v37, 0x62, v42
	v_sub_u32_e32 v40, v37, v110
	v_sub_u32_e32 v37, v110, v37
	v_cndmask_b32_e64 v37, v40, v37, s[2:3]
	v_cmp_lt_i32_e64 s[66:67], -1, v37
	v_cvt_f32_u32_e32 v37, v37
	v_mul_f32_e32 v37, v38, v37
	v_exp_f32_e32 v187, v37
	v_or_b32_e32 v37, 0x63, v42
	v_sub_u32_e32 v40, v37, v110
	v_sub_u32_e32 v37, v110, v37
	v_cndmask_b32_e64 v37, v40, v37, s[2:3]
	v_cmp_lt_i32_e64 s[68:69], -1, v37
	v_cvt_f32_u32_e32 v37, v37
	v_mul_f32_e32 v37, v38, v37
	v_exp_f32_e32 v188, v37
	v_or_b32_e32 v37, 0x70, v42
	v_sub_u32_e32 v40, v37, v110
	v_sub_u32_e32 v37, v110, v37
	v_cndmask_b32_e64 v37, v40, v37, s[2:3]
	v_cmp_lt_i32_e64 s[70:71], -1, v37
	v_cvt_f32_u32_e32 v37, v37
	v_mul_f32_e32 v37, v38, v37
	v_exp_f32_e32 v189, v37
	v_or_b32_e32 v37, 0x71, v42
	v_sub_u32_e32 v40, v37, v110
	v_sub_u32_e32 v37, v110, v37
	v_cndmask_b32_e64 v37, v40, v37, s[2:3]
	v_cmp_lt_i32_e64 s[72:73], -1, v37
	v_cvt_f32_u32_e32 v37, v37
	v_mul_f32_e32 v37, v38, v37
	v_exp_f32_e32 v190, v37
	v_or_b32_e32 v37, 0x72, v42
	v_sub_u32_e32 v40, v37, v110
	v_sub_u32_e32 v37, v110, v37
	v_cndmask_b32_e64 v37, v40, v37, s[2:3]
	v_cmp_lt_i32_e64 s[74:75], -1, v37
	v_cvt_f32_u32_e32 v37, v37
	v_mul_f32_e32 v37, v38, v37
	v_exp_f32_e32 v191, v37
	v_or_b32_e32 v37, 0x73, v42
	v_sub_u32_e32 v40, v37, v110
	v_sub_u32_e32 v37, v110, v37
	v_cndmask_b32_e64 v37, v40, v37, s[2:3]
	v_cmp_lt_i32_e64 s[76:77], -1, v37
	v_cvt_f32_u32_e32 v37, v37
	v_mov_b32_e32 v40, v109
	v_mov_b32_e32 v42, v109
	v_mul_f32_e32 v37, v38, v37
	v_exp_f32_e32 v192, v37
	v_mad_u32_u24 v37, v27, s84, v163
	v_mul_u32_u24_e32 v27, 0x110, v39
	v_add3_u32 v203, 0, v27, v108
	v_mov_b32_e32 v27, v109
	v_lshl_add_u64 v[142:143], s[78:79], 0, v[26:27]
	s_add_u32 s78, s82, s80
	s_addc_u32 s79, s83, 0
	s_add_u32 s78, s78, s81
	v_mul_lo_u32 v38, v43, s85
	s_addc_u32 s79, s79, 0
	v_lshl_add_u64 v[144:145], s[78:79], 0, v[108:109]
	v_lshlrev_b32_e32 v108, 1, v24
	v_add_u32_e32 v212, v30, v38
	v_mov_b64_e32 v[24:25], v[56:57]
	v_mov_b64_e32 v[28:29], v[56:57]
	v_add_u32_e32 v211, v128, v37
	v_mov_b64_e32 v[26:27], v[58:59]
	v_mov_b64_e32 v[30:31], v[58:59]
	v_mov_b32_e32 v43, v109
	v_mov_b32_e32 v37, v109
	v_mov_b32_e32 v38, v109
	v_mov_b32_e32 v39, v109
	s_branch .LBB0_775

; __global__ void __launch_bounds__(512, 2) fwd_megakernel(Params p) {
;     ...
;     for (int item = blockIdx.x; item < 256; item += gridDim.x) retention_item(lds, p, item);
;     { EpiFour e; e.CAT = Abuf; e.YCH = (const float*)(ws + OFF_YCH); run_gemm(lds, (const bf16_t*)(ws + OFF_TT), (const bf16_t*)(ws + OFF_YT), 2048, 16384, 2048, e); }
.LBB0_810:
	s_setprio 0
	v_readlane_b32 s0, v255, 2
	v_readlane_b32 s68, v254, 62
	s_waitcnt vmcnt(3)
	v_mov_b32_e32 v8, v200
	v_readlane_b32 s1, v255, 3
	v_readlane_b32 s60, v254, 16
	v_readlane_b32 s64, v254, 20
	v_readlane_b32 s66, v254, 39
	v_readlane_b32 s69, v254, 63
	v_readlane_b32 s72, v254, 51
	v_readlane_b32 s74, v254, 57
	v_readlane_b32 s78, v254, 41
	v_readlane_b32 s80, v254, 55
	s_andn2_b64 vcc, exec, s[0:1]
	v_readfirstlane_b32 s20, v8
	v_readlane_b32 s61, v254, 17
	v_readlane_b32 s62, v254, 18
	v_readlane_b32 s63, v254, 19
	v_readlane_b32 s65, v254, 21
	v_readlane_b32 s67, v254, 40
	v_readlane_b32 s69, v254, 61
	v_readlane_b32 s70, v255, 6
	v_readlane_b32 s73, v254, 52
	v_readlane_b32 s75, v254, 58
	v_readlane_b32 s71, v254, 43
	v_readlane_b32 s79, v254, 42
	v_readlane_b32 s81, v254, 56
	s_cbranch_vccnz .LBB0_831
	s_ashr_i32 s21, s71, 31
	s_lshr_b32 s0, s21, 29
	s_add_i32 s3, s71, s0
	s_and_b32 s0, s3, -8
	s_sub_i32 s4, s71, s0
	s_cmp_gt_i32 s4, -1
	s_cbranch_scc0 .LBB0_813
	s_lshl_b32 s2, s4, 6
	s_mov_b64 s[0:1], 0
	s_branch .LBB0_814
